# LRU pass 1: depthwise conv loads batched as in the final pass
# speedup vs baseline: 1.0569x; 1.0066x over previous
; __device__ __forceinline__ unsigned cvt_pk_bf16(float lo, float hi) { f32x2_t v = {lo, hi}; bf2_t r = __builtin_convertvector(v, bf2_t); return __builtin_bit_cast(unsigned, r); }
; template <bool FINAL>
; __device__ __forceinline__ void lru_item(const Ctx& C, int l, int item) {
;     ...
;     bf16x8 Bw[2][4][2];
; #pragma unroll
;         for (int ty = 0; ty < 2; ++ty)
; #pragma unroll
;             for (int ks = 0; ks < 2; ++ks) {
;                 const float* wp = (ty ? C.P->in[9] : C.P->in[7]) + ((size_t)((l * 2 + z) * 4 + n) * 64 + 32 * ks + 8 * quad) * 64 + fr;
;                 asm volatile("" : "+v"(wp));
;                 float f[4][8];
; #pragma unroll
;                 for (int dt = 0; dt < 4; ++dt)
; #pragma unroll
;                     for (int e = 0; e < 8; ++e) f[dt][e] = wp[e * 64 + 16 * dt];
; #pragma unroll
;                 for (int dt = 0; dt < 4; ++dt) {
;                     union { bf16x8 v; unsigned u[4]; } t_; t_.u[0] = cvt_pk_bf16(f[dt][0], f[dt][1]); t_.u[1] = cvt_pk_bf16(f[dt][2], f[dt][3]); t_.u[2] = cvt_pk_bf16(f[dt][4], f[dt][5]); t_.u[3] = cvt_pk_bf16(f[dt][6], f[dt][7]); Bw[ty][dt][ks] = t_.v; }
;                 asm volatile("" ::: "memory");
;             }
;     {
;         int ch = tid & 255; asm volatile("" : "+v"(ch)); const int hf = tid >> 8;
;         const float w0 = C.P->in[5][(l * 4 + 0) * 256 + ch], w1 = C.P->in[5][(l * 4 + 1) * 256 + ch], w2 = C.P->in[5][(l * 4 + 2) * 256 + ch], w3 = C.P->in[5][(l * 4 + 3) * 256 + ch], cb = C.P->in[6][l * 256 + ch];
.LBB0_435:
	v_mov_b64_e32 v[0:1], v[78:79]
	flat_load_dword v6, v[0:1]
	flat_load_dword v9, v[0:1] offset:256
	flat_load_dword v7, v[0:1] offset:64
	flat_load_dword v10, v[0:1] offset:320
	flat_load_dword v8, v[0:1] offset:128
	flat_load_dword v11, v[0:1] offset:384
	flat_load_dword v12, v[0:1] offset:448
	flat_load_dword v13, v[0:1] offset:192
	flat_load_dword v28, v[0:1] offset:512
	flat_load_dword v34, v[0:1] offset:768
	flat_load_dword v20, v[0:1] offset:576
	flat_load_dword v21, v[0:1] offset:832
	flat_load_dword v16, v[0:1] offset:640
	flat_load_dword v17, v[0:1] offset:896
	flat_load_dword v14, v[0:1] offset:960
	flat_load_dword v15, v[0:1] offset:704
	flat_load_dword v40, v[0:1] offset:1024
	flat_load_dword v42, v[0:1] offset:1280
	flat_load_dword v36, v[0:1] offset:1088
	flat_load_dword v37, v[0:1] offset:1344
	flat_load_dword v22, v[0:1] offset:1152
	flat_load_dword v23, v[0:1] offset:1408
	flat_load_dword v18, v[0:1] offset:1472
	flat_load_dword v19, v[0:1] offset:1216
	flat_load_dword v48, v[0:1] offset:1536
	flat_load_dword v50, v[0:1] offset:1792
	flat_load_dword v44, v[0:1] offset:1600
	flat_load_dword v45, v[0:1] offset:1856
	flat_load_dword v38, v[0:1] offset:1664
	flat_load_dword v39, v[0:1] offset:1920
	flat_load_dword v24, v[0:1] offset:1984
	flat_load_dword v29, v[0:1] offset:1728
	v_mov_b64_e32 v[0:1], v[80:81]
	flat_load_dword v25, v[0:1]
	flat_load_dword v30, v[0:1] offset:256
	flat_load_dword v26, v[0:1] offset:64
	flat_load_dword v31, v[0:1] offset:320
	flat_load_dword v27, v[0:1] offset:128
	flat_load_dword v32, v[0:1] offset:384
	flat_load_dword v33, v[0:1] offset:448
	flat_load_dword v35, v[0:1] offset:192
	flat_load_dword v60, v[0:1] offset:512
	flat_load_dword v68, v[0:1] offset:768
	flat_load_dword v52, v[0:1] offset:576
	flat_load_dword v53, v[0:1] offset:832
	flat_load_dword v46, v[0:1] offset:640
	flat_load_dword v47, v[0:1] offset:896
	flat_load_dword v41, v[0:1] offset:960
	flat_load_dword v43, v[0:1] offset:704
	flat_load_dword v74, v[0:1] offset:1024
	flat_load_dword v76, v[0:1] offset:1280
	flat_load_dword v70, v[0:1] offset:1088
	flat_load_dword v71, v[0:1] offset:1344
	flat_load_dword v54, v[0:1] offset:1152
	flat_load_dword v55, v[0:1] offset:1408
	flat_load_dword v49, v[0:1] offset:1472
	flat_load_dword v51, v[0:1] offset:1216
	flat_load_dword v102, v[0:1] offset:1536
	flat_load_dword v104, v[0:1] offset:1792
	flat_load_dword v98, v[0:1] offset:1600
	flat_load_dword v99, v[0:1] offset:1856
	flat_load_dword v72, v[0:1] offset:1664
	flat_load_dword v73, v[0:1] offset:1920
	flat_load_dword v56, v[0:1] offset:1984
	flat_load_dword v61, v[0:1] offset:1728
	v_mov_b64_e32 v[0:1], v[82:83]
	flat_load_dword v57, v[0:1]
	flat_load_dword v62, v[0:1] offset:256
	flat_load_dword v58, v[0:1] offset:64
	flat_load_dword v63, v[0:1] offset:320
	flat_load_dword v59, v[0:1] offset:128
	flat_load_dword v66, v[0:1] offset:384
	flat_load_dword v67, v[0:1] offset:448
	flat_load_dword v69, v[0:1] offset:192
	flat_load_dword v174, v[0:1] offset:512
	flat_load_dword v194, v[0:1] offset:768
	flat_load_dword v166, v[0:1] offset:576
	flat_load_dword v167, v[0:1] offset:832
	flat_load_dword v100, v[0:1] offset:640
	flat_load_dword v101, v[0:1] offset:896
	flat_load_dword v75, v[0:1] offset:960
	flat_load_dword v77, v[0:1] offset:704
	flat_load_dword v200, v[0:1] offset:1024
	flat_load_dword v202, v[0:1] offset:1280
	flat_load_dword v196, v[0:1] offset:1088
	flat_load_dword v197, v[0:1] offset:1344
	flat_load_dword v168, v[0:1] offset:1152
	flat_load_dword v169, v[0:1] offset:1408
	flat_load_dword v103, v[0:1] offset:1472
	flat_load_dword v105, v[0:1] offset:1216
	flat_load_dword v208, v[0:1] offset:1536
	flat_load_dword v210, v[0:1] offset:1792
	flat_load_dword v204, v[0:1] offset:1600
	flat_load_dword v205, v[0:1] offset:1856
	flat_load_dword v198, v[0:1] offset:1664
	flat_load_dword v199, v[0:1] offset:1920
	flat_load_dword v170, v[0:1] offset:1984
	flat_load_dword v175, v[0:1] offset:1728
	v_mov_b64_e32 v[0:1], v[84:85]
	flat_load_dword v171, v[0:1]
	flat_load_dword v176, v[0:1] offset:256
	flat_load_dword v172, v[0:1] offset:64
	flat_load_dword v177, v[0:1] offset:320
	flat_load_dword v173, v[0:1] offset:128
	flat_load_dword v192, v[0:1] offset:384
	flat_load_dword v193, v[0:1] offset:448
	flat_load_dword v195, v[0:1] offset:192
	flat_load_dword v229, v[0:1] offset:512
	flat_load_dword v231, v[0:1] offset:768
	flat_load_dword v212, v[0:1] offset:576
	flat_load_dword v213, v[0:1] offset:832
	flat_load_dword v206, v[0:1] offset:640
	flat_load_dword v207, v[0:1] offset:896
	flat_load_dword v201, v[0:1] offset:960
	flat_load_dword v203, v[0:1] offset:704
	flat_load_dword v236, v[0:1] offset:1024
	flat_load_dword v237, v[0:1] offset:1280
	flat_load_dword v232, v[0:1] offset:1088
	flat_load_dword v233, v[0:1] offset:1344
	flat_load_dword v214, v[0:1] offset:1152
	flat_load_dword v215, v[0:1] offset:1408
	flat_load_dword v209, v[0:1] offset:1472
	flat_load_dword v211, v[0:1] offset:1216
	flat_load_dword v240, v[0:1] offset:1536
	flat_load_dword v241, v[0:1] offset:1792
	flat_load_dword v238, v[0:1] offset:1600
	flat_load_dword v239, v[0:1] offset:1856
	flat_load_dword v234, v[0:1] offset:1664
	flat_load_dword v235, v[0:1] offset:1920
	flat_load_dword v228, v[0:1] offset:1984
	flat_load_dword v230, v[0:1] offset:1728
	v_mov_b32_e32 v4, v95
	v_readlane_b32 s0, v254, 63
	v_readlane_b32 s78, v251, 14
	v_readlane_b32 s79, v251, 15
	v_readlane_b32 s80, v251, 16
	v_readlane_b32 s81, v251, 17
	v_add_u32_e32 v0, s0, v4
	v_ashrrev_i32_e32 v1, 31, v0
	v_lshl_add_u64 v[2:3], v[0:1], 2, s[78:79]
	v_add_u32_e32 v0, s40, v0
; __device__ __forceinline__ bf16_t f2bf(float f) { return (bf16_t)(cvt_pk_bf16(f, 0.f) & 0xffffu); }
; __device__ __forceinline__ float bf2f(bf16_t b) { return __uint_as_float(((unsigned)b) << 16); }
; template <bool FINAL>
; __device__ __forceinline__ void lru_item(const Ctx& C, int l, int item) {
;     ...
;         const int tl0 = hf * 32, t0 = c * 64 + tl0;
;         const bf16_t* colp = pb + (size_t)(b * SEQ) * 512 + ch;
;         float xm2 = (t0 - 2 >= 0) ? bf2f(colp[(size_t)(t0 - 2) * 512]) : 0.f, xm1 = (t0 - 1 >= 0) ? bf2f(colp[(size_t)(t0 - 1) * 512]) : 0.f, x0 = bf2f(colp[(size_t)t0 * 512]);
; #pragma unroll 1
;         for (int k8 = 0; k8 < 4; ++k8) { float xn[8];
; #pragma unroll
;             for (int k = 0; k < 8; ++k) { const int t = t0 + k8 * 8 + k + 1; xn[k] = (t < SEQ) ? bf2f(colp[(size_t)t * 512]) : 0.f; }
; #pragma unroll
;             for (int k = 0; k < 8; ++k) { xc[(tl0 + k8 * 8 + k) * XCP + ch] = f2bf(cb + w0 * xm2 + w1 * xm1 + w2 * x0 + w3 * xn[k]); xm2 = xm1; xm1 = x0; x0 = xn[k]; } }
	global_load_dword v155, v[2:3], off
	global_load_dword v156, v[2:3], off offset:1024
	global_load_dword v157, v[2:3], off offset:2048
	global_load_dword v158, v[2:3], off offset:3072
	v_ashrrev_i32_e32 v1, 31, v0
	v_lshl_add_u64 v[0:1], v[0:1], 2, s[80:81]
	global_load_dword v159, v[0:1], off
	s_lshl_b32 s0, s17, 6
	s_and_b32 s0, s0, 0xfffff000
	s_ashr_i32 s1, s0, 31
	s_and_b32 s18, s17, 63
	s_lshl_b64 s[0:1], s[0:1], 10
	s_add_u32 s0, s12, s0
	s_addc_u32 s1, s13, s1
	v_lshl_add_u32 v183, s18, 6, v97
	v_ashrrev_i32_e32 v5, 31, v4
	v_lshl_add_u64 v[0:1], v[4:5], 1, s[0:1]
	v_lshl_add_u32 v64, v4, 1, v135
	s_mov_b64 s[22:23], 0x2000
	v_add_u32_e32 v2, 2, v183
	v_mov_b32_e32 v3, 0
	v_lshlrev_b64 v[2:3], 10, v[2:3]
	v_lshl_add_u64 v[2:3], v[2:3], 0, v[0:1]
	global_load_ushort v4, v[2:3], off offset:-4096
	global_load_ushort v5, v[2:3], off offset:-3072
	global_load_ushort v160, v[2:3], off offset:-2048
	global_load_ushort v161, v[2:3], off offset:-1024
	global_load_ushort v162, v[2:3], off
	global_load_ushort v163, v[2:3], off offset:1024
	global_load_ushort v164, v[2:3], off offset:2048
	global_load_ushort v165, v[2:3], off offset:3072
	v_lshl_add_u64 v[2:3], v[2:3], 0, s[22:23]
	global_load_ushort v178, v[2:3], off offset:-4096
	global_load_ushort v179, v[2:3], off offset:-3072
	global_load_ushort v180, v[2:3], off offset:-2048
	global_load_ushort v181, v[2:3], off offset:-1024
	global_load_ushort v188, v[2:3], off
	global_load_ushort v189, v[2:3], off offset:1024
	global_load_ushort v190, v[2:3], off offset:2048
	global_load_ushort v191, v[2:3], off offset:3072
	v_lshl_add_u64 v[2:3], v[2:3], 0, s[22:23]
	global_load_ushort v223, v[2:3], off offset:-4096
	global_load_ushort v242, v[2:3], off offset:-3072
	global_load_ushort v243, v[2:3], off offset:-2048
	s_movk_i32 s19, 0xfe0
	v_cmp_eq_u32_e32 vcc, 0, v183
	v_cmp_eq_u32_e64 s[0:1], s19, v183
	s_waitcnt vmcnt(0)
	v_cndmask_b32_e64 v4, v4, 0, vcc
	v_cndmask_b32_e64 v5, v5, 0, vcc
	v_lshlrev_b32_e32 v4, 16, v4
	v_lshlrev_b32_e32 v5, 16, v5
	v_lshlrev_b32_e32 v160, 16, v160
	v_lshlrev_b32_e32 v161, 16, v161
	v_lshlrev_b32_e32 v162, 16, v162
	v_lshlrev_b32_e32 v163, 16, v163
	v_lshlrev_b32_e32 v164, 16, v164
	v_lshlrev_b32_e32 v165, 16, v165
	v_lshlrev_b32_e32 v178, 16, v178
	v_lshlrev_b32_e32 v179, 16, v179
	v_lshlrev_b32_e32 v180, 16, v180
	v_lshlrev_b32_e32 v181, 16, v181
	v_lshlrev_b32_e32 v188, 16, v188
	v_lshlrev_b32_e32 v189, 16, v189
	v_lshlrev_b32_e32 v190, 16, v190
	v_lshlrev_b32_e32 v191, 16, v191
	v_lshlrev_b32_e32 v223, 16, v223
	v_lshlrev_b32_e32 v242, 16, v242
	v_lshlrev_b32_e32 v243, 16, v243
	v_fma_f32 v0, v155, v4, v159
	v_fmac_f32_e32 v0, v156, v5
	v_fmac_f32_e32 v0, v157, v160
	v_fmac_f32_e32 v0, v158, v161
	v_cvt_pk_bf16_f32 v0, v0, v0
	ds_write_b16 v64, v0
	v_fma_f32 v1, v155, v5, v159
	v_fmac_f32_e32 v1, v156, v160
	v_fmac_f32_e32 v1, v157, v161
	v_fmac_f32_e32 v1, v158, v162
	v_cvt_pk_bf16_f32 v1, v1, v1
	ds_write_b16 v64, v1 offset:528
	v_fma_f32 v0, v155, v160, v159
	v_fmac_f32_e32 v0, v156, v161
	v_fmac_f32_e32 v0, v157, v162
	v_fmac_f32_e32 v0, v158, v163
	v_cvt_pk_bf16_f32 v0, v0, v0
	ds_write_b16 v64, v0 offset:1056
	v_fma_f32 v1, v155, v161, v159
	v_fmac_f32_e32 v1, v156, v162
	v_fmac_f32_e32 v1, v157, v163
	v_fmac_f32_e32 v1, v158, v164
	v_cvt_pk_bf16_f32 v1, v1, v1
	ds_write_b16 v64, v1 offset:1584
	v_fma_f32 v0, v155, v162, v159
	v_fmac_f32_e32 v0, v156, v163
	v_fmac_f32_e32 v0, v157, v164
	v_fmac_f32_e32 v0, v158, v165
	v_cvt_pk_bf16_f32 v0, v0, v0
	ds_write_b16 v64, v0 offset:2112
	v_fma_f32 v1, v155, v163, v159
	v_fmac_f32_e32 v1, v156, v164
	v_fmac_f32_e32 v1, v157, v165
	v_fmac_f32_e32 v1, v158, v178
	v_cvt_pk_bf16_f32 v1, v1, v1
	ds_write_b16 v64, v1 offset:2640
	v_fma_f32 v0, v155, v164, v159
	v_fmac_f32_e32 v0, v156, v165
	v_fmac_f32_e32 v0, v157, v178
	v_fmac_f32_e32 v0, v158, v179
	v_cvt_pk_bf16_f32 v0, v0, v0
	ds_write_b16 v64, v0 offset:3168
	v_fma_f32 v1, v155, v165, v159
	v_fmac_f32_e32 v1, v156, v178
	v_fmac_f32_e32 v1, v157, v179
	v_fmac_f32_e32 v1, v158, v180
	v_cvt_pk_bf16_f32 v1, v1, v1
	ds_write_b16 v64, v1 offset:3696
	v_fma_f32 v0, v155, v178, v159
	v_fmac_f32_e32 v0, v156, v179
	v_fmac_f32_e32 v0, v157, v180
	v_fmac_f32_e32 v0, v158, v181
	v_cvt_pk_bf16_f32 v0, v0, v0
	ds_write_b16 v64, v0 offset:4224
	v_fma_f32 v1, v155, v179, v159
	v_fmac_f32_e32 v1, v156, v180
	v_fmac_f32_e32 v1, v157, v181
	v_fmac_f32_e32 v1, v158, v188
	v_cvt_pk_bf16_f32 v1, v1, v1
	ds_write_b16 v64, v1 offset:4752
	v_fma_f32 v0, v155, v180, v159
	v_fmac_f32_e32 v0, v156, v181
	v_fmac_f32_e32 v0, v157, v188
	v_fmac_f32_e32 v0, v158, v189
	v_cvt_pk_bf16_f32 v0, v0, v0
	ds_write_b16 v64, v0 offset:5280
	v_fma_f32 v1, v155, v181, v159
	v_fmac_f32_e32 v1, v156, v188
	v_fmac_f32_e32 v1, v157, v189
	v_fmac_f32_e32 v1, v158, v190
	v_cvt_pk_bf16_f32 v1, v1, v1
	ds_write_b16 v64, v1 offset:5808
	v_fma_f32 v0, v155, v188, v159
	v_fmac_f32_e32 v0, v156, v189
	v_fmac_f32_e32 v0, v157, v190
	v_fmac_f32_e32 v0, v158, v191
	v_cvt_pk_bf16_f32 v0, v0, v0
	ds_write_b16 v64, v0 offset:6336
	v_fma_f32 v1, v155, v189, v159
	v_fmac_f32_e32 v1, v156, v190
	v_fmac_f32_e32 v1, v157, v191
	v_fmac_f32_e32 v1, v158, v223
	v_cvt_pk_bf16_f32 v1, v1, v1
	ds_write_b16 v64, v1 offset:6864
	v_fma_f32 v0, v155, v190, v159
	v_fmac_f32_e32 v0, v156, v191
	v_fmac_f32_e32 v0, v157, v223
	v_fmac_f32_e32 v0, v158, v242
	v_cvt_pk_bf16_f32 v0, v0, v0
	ds_write_b16 v64, v0 offset:7392
	v_fma_f32 v1, v155, v191, v159
	v_fmac_f32_e32 v1, v156, v223
	v_fmac_f32_e32 v1, v157, v242
	v_fmac_f32_e32 v1, v158, v243
	v_cvt_pk_bf16_f32 v1, v1, v1
	ds_write_b16 v64, v1 offset:7920
	global_load_ushort v4, v[2:3], off offset:-1024
	global_load_ushort v5, v[2:3], off
	global_load_ushort v160, v[2:3], off offset:1024
	global_load_ushort v161, v[2:3], off offset:2048
	global_load_ushort v162, v[2:3], off offset:3072
	v_lshl_add_u64 v[2:3], v[2:3], 0, s[22:23]
	global_load_ushort v163, v[2:3], off offset:-4096
	global_load_ushort v164, v[2:3], off offset:-3072
	global_load_ushort v165, v[2:3], off offset:-2048
	global_load_ushort v178, v[2:3], off offset:-1024
	global_load_ushort v179, v[2:3], off
	global_load_ushort v180, v[2:3], off offset:1024
	global_load_ushort v181, v[2:3], off offset:2048
	global_load_ushort v188, v[2:3], off offset:3072
	v_lshl_add_u64 v[2:3], v[2:3], 0, s[22:23]
	global_load_ushort v189, v[2:3], off offset:-4096
	global_load_ushort v190, v[2:3], off offset:-3072
	global_load_ushort v191, v[2:3], off offset:-2048
	s_waitcnt vmcnt(0)
; __device__ __forceinline__ bf16_t f2bf(float f) { return (bf16_t)(cvt_pk_bf16(f, 0.f) & 0xffffu); }
; __device__ __forceinline__ float bf2f(bf16_t b) { return __uint_as_float(((unsigned)b) << 16); }
; template <bool FINAL>
; __device__ __forceinline__ void lru_item(const Ctx& C, int l, int item) {
;     ...
;         for (int k8 = 0; k8 < 4; ++k8) { float xn[8];
; #pragma unroll
;             for (int k = 0; k < 8; ++k) { const int t = t0 + k8 * 8 + k + 1; xn[k] = (t < SEQ) ? bf2f(colp[(size_t)t * 512]) : 0.f; }
; #pragma unroll
;             for (int k = 0; k < 8; ++k) { xc[(tl0 + k8 * 8 + k) * XCP + ch] = f2bf(cb + w0 * xm2 + w1 * xm1 + w2 * x0 + w3 * xn[k]); xm2 = xm1; xm1 = x0; x0 = xn[k]; } }
	v_cndmask_b32_e64 v191, v191, 0, s[0:1]
	v_lshlrev_b32_e32 v4, 16, v4
	v_lshlrev_b32_e32 v5, 16, v5
	v_lshlrev_b32_e32 v160, 16, v160
	v_lshlrev_b32_e32 v161, 16, v161
	v_lshlrev_b32_e32 v162, 16, v162
	v_lshlrev_b32_e32 v163, 16, v163
	v_lshlrev_b32_e32 v164, 16, v164
	v_lshlrev_b32_e32 v165, 16, v165
	v_lshlrev_b32_e32 v178, 16, v178
	v_lshlrev_b32_e32 v179, 16, v179
	v_lshlrev_b32_e32 v180, 16, v180
	v_lshlrev_b32_e32 v181, 16, v181
	v_lshlrev_b32_e32 v188, 16, v188
	v_lshlrev_b32_e32 v189, 16, v189
	v_lshlrev_b32_e32 v190, 16, v190
	v_lshlrev_b32_e32 v191, 16, v191
	v_fma_f32 v0, v155, v223, v159
	v_fmac_f32_e32 v0, v156, v242
	v_fmac_f32_e32 v0, v157, v243
	v_fmac_f32_e32 v0, v158, v4
	v_cvt_pk_bf16_f32 v0, v0, v0
	ds_write_b16 v64, v0 offset:8448
	v_fma_f32 v1, v155, v242, v159
	v_fmac_f32_e32 v1, v156, v243
	v_fmac_f32_e32 v1, v157, v4
	v_fmac_f32_e32 v1, v158, v5
	v_cvt_pk_bf16_f32 v1, v1, v1
	ds_write_b16 v64, v1 offset:8976
	v_fma_f32 v0, v155, v243, v159
	v_fmac_f32_e32 v0, v156, v4
	v_fmac_f32_e32 v0, v157, v5
	v_fmac_f32_e32 v0, v158, v160
	v_cvt_pk_bf16_f32 v0, v0, v0
	ds_write_b16 v64, v0 offset:9504
	v_fma_f32 v1, v155, v4, v159
	v_fmac_f32_e32 v1, v156, v5
	v_fmac_f32_e32 v1, v157, v160
	v_fmac_f32_e32 v1, v158, v161
	v_cvt_pk_bf16_f32 v1, v1, v1
	ds_write_b16 v64, v1 offset:10032
	v_fma_f32 v0, v155, v5, v159
	v_fmac_f32_e32 v0, v156, v160
	v_fmac_f32_e32 v0, v157, v161
	v_fmac_f32_e32 v0, v158, v162
	v_cvt_pk_bf16_f32 v0, v0, v0
	ds_write_b16 v64, v0 offset:10560
	v_fma_f32 v1, v155, v160, v159
	v_fmac_f32_e32 v1, v156, v161
	v_fmac_f32_e32 v1, v157, v162
	v_fmac_f32_e32 v1, v158, v163
	v_cvt_pk_bf16_f32 v1, v1, v1
	ds_write_b16 v64, v1 offset:11088
	v_fma_f32 v0, v155, v161, v159
	v_fmac_f32_e32 v0, v156, v162
	v_fmac_f32_e32 v0, v157, v163
	v_fmac_f32_e32 v0, v158, v164
	v_cvt_pk_bf16_f32 v0, v0, v0
	ds_write_b16 v64, v0 offset:11616
	v_fma_f32 v1, v155, v162, v159
	v_fmac_f32_e32 v1, v156, v163
	v_fmac_f32_e32 v1, v157, v164
	v_fmac_f32_e32 v1, v158, v165
	v_cvt_pk_bf16_f32 v1, v1, v1
	ds_write_b16 v64, v1 offset:12144
	v_fma_f32 v0, v155, v163, v159
	v_fmac_f32_e32 v0, v156, v164
	v_fmac_f32_e32 v0, v157, v165
	v_fmac_f32_e32 v0, v158, v178
	v_cvt_pk_bf16_f32 v0, v0, v0
	ds_write_b16 v64, v0 offset:12672
	v_fma_f32 v1, v155, v164, v159
	v_fmac_f32_e32 v1, v156, v165
	v_fmac_f32_e32 v1, v157, v178
	v_fmac_f32_e32 v1, v158, v179
	v_cvt_pk_bf16_f32 v1, v1, v1
	ds_write_b16 v64, v1 offset:13200
	v_fma_f32 v0, v155, v165, v159
	v_fmac_f32_e32 v0, v156, v178
	v_fmac_f32_e32 v0, v157, v179
	v_fmac_f32_e32 v0, v158, v180
	v_cvt_pk_bf16_f32 v0, v0, v0
	ds_write_b16 v64, v0 offset:13728
	v_fma_f32 v1, v155, v178, v159
	v_fmac_f32_e32 v1, v156, v179
	v_fmac_f32_e32 v1, v157, v180
	v_fmac_f32_e32 v1, v158, v181
	v_cvt_pk_bf16_f32 v1, v1, v1
	ds_write_b16 v64, v1 offset:14256
	v_fma_f32 v0, v155, v179, v159
	v_fmac_f32_e32 v0, v156, v180
	v_fmac_f32_e32 v0, v157, v181
	v_fmac_f32_e32 v0, v158, v188
	v_cvt_pk_bf16_f32 v0, v0, v0
	ds_write_b16 v64, v0 offset:14784
	v_fma_f32 v1, v155, v180, v159
	v_fmac_f32_e32 v1, v156, v181
	v_fmac_f32_e32 v1, v157, v188
	v_fmac_f32_e32 v1, v158, v189
	v_cvt_pk_bf16_f32 v1, v1, v1
	ds_write_b16 v64, v1 offset:15312
	v_fma_f32 v0, v155, v181, v159
	v_fmac_f32_e32 v0, v156, v188
	v_fmac_f32_e32 v0, v157, v189
	v_fmac_f32_e32 v0, v158, v190
	v_cvt_pk_bf16_f32 v0, v0, v0
	ds_write_b16 v64, v0 offset:15840
	v_fma_f32 v1, v155, v188, v159
	v_fmac_f32_e32 v1, v156, v189
	v_fmac_f32_e32 v1, v157, v190
	v_fmac_f32_e32 v1, v158, v191
	v_cvt_pk_bf16_f32 v1, v1, v1
	ds_write_b16 v64, v1 offset:16368
